# adds phase_mod (adaLN modulation GEMV) inner loop with a 4-deep ring of weight-row loads (3 iterations of lookahead)
# baseline (speedup 1.0000x reference)
; DI void phase_mod(CP p, LAS unsigned char* lds) {
;     ...
;     for (int task = blockIdx.x; task < 4 * 96; task += gridDim.x) {
;         const int l = task / 96, nb = task - l * 96, n = nb * 64 + lane;
;         const float* W = p->w_ada + (size_t)l * 1024 * 6144 + n;
;         float acc[8];
; #pragma unroll
;         for (int b = 0; b < 8; ++b) acc[b] = 0.f;
;         const int k0 = wave * 128;
; #pragma unroll 8
;         for (int k = k0; k < k0 + 128; ++k) { const float w = W[(size_t)k * 6144];
; #pragma unroll
;             for (int b = 0; b < 8; ++b) acc[b] += ca[b * 1024 + k] * w; }
.LBB0_11:
	s_mov_b32 s100, 0x0
	s_mov_b32 s101, 0
	v_lshl_add_u64 v[86:87], v[36:37], 0, s[100:101]
	v_add_co_u32_e32 v88, vcc, s11, v86
	s_nop 1
	v_addc_co_u32_e32 v89, vcc, 0, v87, vcc
	v_add_co_u32_e32 v90, vcc, s15, v86
	s_nop 1
	v_addc_co_u32_e32 v91, vcc, 0, v87, vcc
	v_add_co_u32_e32 v92, vcc, s16, v86
	s_nop 1
	v_addc_co_u32_e32 v93, vcc, 0, v87, vcc
	v_add_co_u32_e32 v94, vcc, s17, v86
	s_nop 1
	v_addc_co_u32_e32 v95, vcc, 0, v87, vcc
	v_add_co_u32_e32 v96, vcc, s18, v86
	s_nop 1
	v_addc_co_u32_e32 v97, vcc, 0, v87, vcc
	v_add_co_u32_e32 v98, vcc, s19, v86
	s_nop 1
	v_addc_co_u32_e32 v99, vcc, 0, v87, vcc
	global_load_dword v100, v[86:87], off
	global_load_dword v102, v[88:89], off
	global_load_dword v104, v[90:91], off
	global_load_dword v106, v[92:93], off
	global_load_dword v108, v[94:95], off
	global_load_dword v110, v[96:97], off
	global_load_dword v112, v[98:99], off
	v_add_co_u32_e32 v86, vcc, s20, v86
	s_nop 1
	v_addc_co_u32_e32 v87, vcc, 0, v87, vcc
	global_load_dword v114, v[86:87], off
	s_mov_b32 s100, 0x30000
	s_mov_b32 s101, 0
	v_lshl_add_u64 v[86:87], v[36:37], 0, s[100:101]
	v_add_co_u32_e32 v88, vcc, s11, v86
	s_nop 1
	v_addc_co_u32_e32 v89, vcc, 0, v87, vcc
	v_add_co_u32_e32 v90, vcc, s15, v86
	s_nop 1
	v_addc_co_u32_e32 v91, vcc, 0, v87, vcc
	v_add_co_u32_e32 v92, vcc, s16, v86
	s_nop 1
	v_addc_co_u32_e32 v93, vcc, 0, v87, vcc
	v_add_co_u32_e32 v94, vcc, s17, v86
	s_nop 1
	v_addc_co_u32_e32 v95, vcc, 0, v87, vcc
	v_add_co_u32_e32 v96, vcc, s18, v86
	s_nop 1
	v_addc_co_u32_e32 v97, vcc, 0, v87, vcc
	v_add_co_u32_e32 v98, vcc, s19, v86
	s_nop 1
	v_addc_co_u32_e32 v99, vcc, 0, v87, vcc
	global_load_dword v116, v[86:87], off
	global_load_dword v118, v[88:89], off
	global_load_dword v120, v[90:91], off
	global_load_dword v122, v[92:93], off
	global_load_dword v124, v[94:95], off
	global_load_dword v126, v[96:97], off
	global_load_dword v128, v[98:99], off
	v_add_co_u32_e32 v86, vcc, s20, v86
	s_nop 1
	v_addc_co_u32_e32 v87, vcc, 0, v87, vcc
	global_load_dword v130, v[86:87], off
	s_mov_b32 s100, 0x60000
	s_mov_b32 s101, 0
	v_lshl_add_u64 v[86:87], v[36:37], 0, s[100:101]
	v_add_co_u32_e32 v88, vcc, s11, v86
	s_nop 1
	v_addc_co_u32_e32 v89, vcc, 0, v87, vcc
	v_add_co_u32_e32 v90, vcc, s15, v86
	s_nop 1
	v_addc_co_u32_e32 v91, vcc, 0, v87, vcc
	v_add_co_u32_e32 v92, vcc, s16, v86
	s_nop 1
	v_addc_co_u32_e32 v93, vcc, 0, v87, vcc
	v_add_co_u32_e32 v94, vcc, s17, v86
	s_nop 1
	v_addc_co_u32_e32 v95, vcc, 0, v87, vcc
	v_add_co_u32_e32 v96, vcc, s18, v86
	s_nop 1
	v_addc_co_u32_e32 v97, vcc, 0, v87, vcc
	v_add_co_u32_e32 v98, vcc, s19, v86
	s_nop 1
	v_addc_co_u32_e32 v99, vcc, 0, v87, vcc
	global_load_dword v132, v[86:87], off
	global_load_dword v134, v[88:89], off
	global_load_dword v136, v[90:91], off
	global_load_dword v138, v[92:93], off
	global_load_dword v140, v[94:95], off
	global_load_dword v142, v[96:97], off
	global_load_dword v144, v[98:99], off
	v_add_co_u32_e32 v86, vcc, s20, v86
	s_nop 1
	v_addc_co_u32_e32 v87, vcc, 0, v87, vcc
	global_load_dword v146, v[86:87], off
.Lmod_loop:
	s_add_u32 s100, s4, 0x90000
	s_min_u32 s100, s100, 0x2d0000
	s_mov_b32 s101, 0
	v_lshl_add_u64 v[86:87], v[36:37], 0, s[100:101]
	v_add_co_u32_e32 v88, vcc, s11, v86
	s_nop 1
	v_addc_co_u32_e32 v89, vcc, 0, v87, vcc
	v_add_co_u32_e32 v90, vcc, s15, v86
	s_nop 1
	v_addc_co_u32_e32 v91, vcc, 0, v87, vcc
	v_add_co_u32_e32 v92, vcc, s16, v86
	s_nop 1
	v_addc_co_u32_e32 v93, vcc, 0, v87, vcc
	v_add_co_u32_e32 v94, vcc, s17, v86
	s_nop 1
	v_addc_co_u32_e32 v95, vcc, 0, v87, vcc
	v_add_co_u32_e32 v96, vcc, s18, v86
	s_nop 1
	v_addc_co_u32_e32 v97, vcc, 0, v87, vcc
	v_add_co_u32_e32 v98, vcc, s19, v86
	s_nop 1
	v_addc_co_u32_e32 v99, vcc, 0, v87, vcc
	global_load_dword v148, v[86:87], off
	global_load_dword v150, v[88:89], off
	global_load_dword v152, v[90:91], off
	global_load_dword v154, v[92:93], off
	global_load_dword v156, v[94:95], off
	global_load_dword v158, v[96:97], off
	global_load_dword v160, v[98:99], off
	v_add_co_u32_e32 v86, vcc, s20, v86
	s_nop 1
	v_addc_co_u32_e32 v87, vcc, 0, v87, vcc
	global_load_dword v162, v[86:87], off
	ds_read_b128 v[10:13], v52
	ds_read_b128 v[6:9], v52 offset:16
	ds_read_b128 v[2:5], v52 offset:4096
	ds_read_b128 v[14:17], v52 offset:4112
	ds_read_b128 v[54:57], v52 offset:8192
	ds_read_b128 v[58:61], v52 offset:8208
	ds_read_b128 v[22:25], v52 offset:12288
	ds_read_b128 v[18:21], v52 offset:12304
	ds_read_b128 v[62:65], v52 offset:16384
	ds_read_b128 v[66:69], v52 offset:16400
	ds_read_b128 v[30:33], v52 offset:20480
	ds_read_b128 v[26:29], v52 offset:20496
	ds_read_b128 v[70:73], v52 offset:24576
	ds_read_b128 v[74:77], v52 offset:24592
	ds_read_b128 v[78:81], v52 offset:28672
	ds_read_b128 v[82:85], v52 offset:28688
	v_add_u32_e32 v52, 32, v52
	s_waitcnt lgkmcnt(14)
	v_mov_b32_e32 v86, v10
	s_waitcnt lgkmcnt(13)
	v_mov_b32_e32 v87, v2
	v_mov_b32_e32 v2, v11
	v_mov_b32_e32 v10, v12
	v_mov_b32_e32 v11, v4
	v_mov_b32_e32 v4, v13
	s_waitcnt lgkmcnt(11)
	v_mov_b32_e32 v12, v54
	s_waitcnt lgkmcnt(9)
	v_mov_b32_e32 v13, v22
	v_mov_b32_e32 v22, v55
	v_mov_b32_e32 v54, v56
	v_mov_b32_e32 v55, v24
	v_mov_b32_e32 v24, v57
	s_waitcnt lgkmcnt(7)
	v_mov_b32_e32 v56, v62
	s_waitcnt lgkmcnt(5)
	v_mov_b32_e32 v57, v30
	v_mov_b32_e32 v30, v63
	v_mov_b32_e32 v62, v64
	v_mov_b32_e32 v63, v32
	v_mov_b32_e32 v32, v65
	s_waitcnt lgkmcnt(3)
	v_mov_b32_e32 v64, v70
	s_waitcnt lgkmcnt(1)
; DI void phase_mod(CP p, LAS unsigned char* lds) {
;     ...
;         for (int k = k0; k < k0 + 128; ++k) { const float w = W[(size_t)k * 6144];
; #pragma unroll
;             for (int b = 0; b < 8; ++b) acc[b] += ca[b * 1024 + k] * w; }
	v_mov_b32_e32 v65, v78
	v_mov_b32_e32 v78, v71
	v_mov_b32_e32 v70, v72
	v_mov_b32_e32 v71, v80
	v_mov_b32_e32 v80, v73
	v_mov_b32_e32 v72, v6
	v_mov_b32_e32 v73, v14
	v_mov_b32_e32 v14, v7
	v_mov_b32_e32 v6, v8
	v_mov_b32_e32 v7, v16
	v_mov_b32_e32 v16, v9
	v_mov_b32_e32 v8, v58
	v_mov_b32_e32 v9, v18
	v_mov_b32_e32 v18, v59
	v_mov_b32_e32 v58, v60
	v_mov_b32_e32 v59, v20
	v_mov_b32_e32 v20, v61
	v_mov_b32_e32 v60, v66
	v_mov_b32_e32 v61, v26
	v_mov_b32_e32 v26, v67
	v_mov_b32_e32 v66, v68
	v_mov_b32_e32 v67, v28
	v_mov_b32_e32 v28, v69
	v_mov_b32_e32 v68, v74
	s_waitcnt lgkmcnt(0)
	v_mov_b32_e32 v69, v82
	v_mov_b32_e32 v82, v75
	v_mov_b32_e32 v74, v76
	v_mov_b32_e32 v75, v84
	v_mov_b32_e32 v84, v77
	s_waitcnt vmcnt(24)
	v_pk_fma_f32 v[40:41], v[100:101], v[86:87], v[40:41] op_sel_hi:[0,1,1]
	v_pk_fma_f32 v[12:13], v[100:101], v[12:13], v[42:43] op_sel_hi:[0,1,1]
	v_pk_fma_f32 v[42:43], v[100:101], v[56:57], v[44:45] op_sel_hi:[0,1,1]
	v_pk_fma_f32 v[38:39], v[100:101], v[64:65], v[38:39] op_sel_hi:[0,1,1]
	v_pk_fma_f32 v[2:3], v[102:103], v[2:3], v[40:41] op_sel_hi:[0,1,1]
	v_pk_fma_f32 v[12:13], v[102:103], v[22:23], v[12:13] op_sel_hi:[0,1,1]
	v_pk_fma_f32 v[22:23], v[102:103], v[30:31], v[42:43] op_sel_hi:[0,1,1]
	v_pk_fma_f32 v[30:31], v[102:103], v[78:79], v[38:39] op_sel_hi:[0,1,1]
	v_pk_fma_f32 v[2:3], v[104:105], v[10:11], v[2:3] op_sel_hi:[0,1,1]
	v_pk_fma_f32 v[10:11], v[104:105], v[54:55], v[12:13] op_sel_hi:[0,1,1]
	v_pk_fma_f32 v[12:13], v[104:105], v[62:63], v[22:23] op_sel_hi:[0,1,1]
	v_pk_fma_f32 v[22:23], v[104:105], v[70:71], v[30:31] op_sel_hi:[0,1,1]
	v_pk_fma_f32 v[2:3], v[106:107], v[4:5], v[2:3] op_sel_hi:[0,1,1]
	v_pk_fma_f32 v[4:5], v[106:107], v[24:25], v[10:11] op_sel_hi:[0,1,1]
	v_pk_fma_f32 v[10:11], v[106:107], v[32:33], v[12:13] op_sel_hi:[0,1,1]
	v_pk_fma_f32 v[12:13], v[106:107], v[80:81], v[22:23] op_sel_hi:[0,1,1]
	v_pk_fma_f32 v[2:3], v[108:109], v[72:73], v[2:3] op_sel_hi:[0,1,1]
	v_pk_fma_f32 v[4:5], v[108:109], v[8:9], v[4:5] op_sel_hi:[0,1,1]
	v_pk_fma_f32 v[8:9], v[108:109], v[60:61], v[10:11] op_sel_hi:[0,1,1]
	v_pk_fma_f32 v[10:11], v[108:109], v[68:69], v[12:13] op_sel_hi:[0,1,1]
	v_pk_fma_f32 v[2:3], v[110:111], v[14:15], v[2:3] op_sel_hi:[0,1,1]
	v_pk_fma_f32 v[4:5], v[110:111], v[18:19], v[4:5] op_sel_hi:[0,1,1]
	v_pk_fma_f32 v[8:9], v[110:111], v[26:27], v[8:9] op_sel_hi:[0,1,1]
	v_pk_fma_f32 v[10:11], v[110:111], v[82:83], v[10:11] op_sel_hi:[0,1,1]
	v_pk_fma_f32 v[2:3], v[112:113], v[6:7], v[2:3] op_sel_hi:[0,1,1]
	v_pk_fma_f32 v[4:5], v[112:113], v[58:59], v[4:5] op_sel_hi:[0,1,1]
	v_pk_fma_f32 v[6:7], v[112:113], v[66:67], v[8:9] op_sel_hi:[0,1,1]
	v_pk_fma_f32 v[8:9], v[112:113], v[74:75], v[10:11] op_sel_hi:[0,1,1]
	v_pk_fma_f32 v[40:41], v[114:115], v[16:17], v[2:3] op_sel_hi:[0,1,1]
	v_pk_fma_f32 v[42:43], v[114:115], v[20:21], v[4:5] op_sel_hi:[0,1,1]
	v_pk_fma_f32 v[44:45], v[114:115], v[28:29], v[6:7] op_sel_hi:[0,1,1]
	v_pk_fma_f32 v[38:39], v[114:115], v[84:85], v[8:9] op_sel_hi:[0,1,1]
	s_add_u32 s4, s4, 0x30000
	s_add_u32 s100, s4, 0x90000
	s_min_u32 s100, s100, 0x2d0000
	s_mov_b32 s101, 0
	v_lshl_add_u64 v[86:87], v[36:37], 0, s[100:101]
	v_add_co_u32_e32 v88, vcc, s11, v86
	s_nop 1
	v_addc_co_u32_e32 v89, vcc, 0, v87, vcc
	v_add_co_u32_e32 v90, vcc, s15, v86
	s_nop 1
	v_addc_co_u32_e32 v91, vcc, 0, v87, vcc
	v_add_co_u32_e32 v92, vcc, s16, v86
	s_nop 1
	v_addc_co_u32_e32 v93, vcc, 0, v87, vcc
	v_add_co_u32_e32 v94, vcc, s17, v86
	s_nop 1
	v_addc_co_u32_e32 v95, vcc, 0, v87, vcc
	v_add_co_u32_e32 v96, vcc, s18, v86
	s_nop 1
	v_addc_co_u32_e32 v97, vcc, 0, v87, vcc
	v_add_co_u32_e32 v98, vcc, s19, v86
	s_nop 1
	v_addc_co_u32_e32 v99, vcc, 0, v87, vcc
	global_load_dword v100, v[86:87], off
	global_load_dword v102, v[88:89], off
	global_load_dword v104, v[90:91], off
	global_load_dword v106, v[92:93], off
	global_load_dword v108, v[94:95], off
	global_load_dword v110, v[96:97], off
	global_load_dword v112, v[98:99], off
	v_add_co_u32_e32 v86, vcc, s20, v86
	s_nop 1
	v_addc_co_u32_e32 v87, vcc, 0, v87, vcc
	global_load_dword v114, v[86:87], off
	ds_read_b128 v[10:13], v52
	ds_read_b128 v[6:9], v52 offset:16
	ds_read_b128 v[2:5], v52 offset:4096
	ds_read_b128 v[14:17], v52 offset:4112
	ds_read_b128 v[54:57], v52 offset:8192
	ds_read_b128 v[58:61], v52 offset:8208
	ds_read_b128 v[22:25], v52 offset:12288
	ds_read_b128 v[18:21], v52 offset:12304
	ds_read_b128 v[62:65], v52 offset:16384
	ds_read_b128 v[66:69], v52 offset:16400
	ds_read_b128 v[30:33], v52 offset:20480
	ds_read_b128 v[26:29], v52 offset:20496
	ds_read_b128 v[70:73], v52 offset:24576
	ds_read_b128 v[74:77], v52 offset:24592
	ds_read_b128 v[78:81], v52 offset:28672
	ds_read_b128 v[82:85], v52 offset:28688
	v_add_u32_e32 v52, 32, v52
	s_waitcnt lgkmcnt(14)
	v_mov_b32_e32 v86, v10
	s_waitcnt lgkmcnt(13)
	v_mov_b32_e32 v87, v2
	v_mov_b32_e32 v2, v11
	v_mov_b32_e32 v10, v12
	v_mov_b32_e32 v11, v4
	v_mov_b32_e32 v4, v13
	s_waitcnt lgkmcnt(11)
	v_mov_b32_e32 v12, v54
	s_waitcnt lgkmcnt(9)
	v_mov_b32_e32 v13, v22
	v_mov_b32_e32 v22, v55
	v_mov_b32_e32 v54, v56
	v_mov_b32_e32 v55, v24
	v_mov_b32_e32 v24, v57
	s_waitcnt lgkmcnt(7)
	v_mov_b32_e32 v56, v62
	s_waitcnt lgkmcnt(5)
	v_mov_b32_e32 v57, v30
	v_mov_b32_e32 v30, v63
	v_mov_b32_e32 v62, v64
	v_mov_b32_e32 v63, v32
	v_mov_b32_e32 v32, v65
	s_waitcnt lgkmcnt(3)
	v_mov_b32_e32 v64, v70
	s_waitcnt lgkmcnt(1)
; DI void phase_mod(CP p, LAS unsigned char* lds) {
;     ...
;         for (int k = k0; k < k0 + 128; ++k) { const float w = W[(size_t)k * 6144];
; #pragma unroll
;             for (int b = 0; b < 8; ++b) acc[b] += ca[b * 1024 + k] * w; }
	v_mov_b32_e32 v65, v78
	v_mov_b32_e32 v78, v71
	v_mov_b32_e32 v70, v72
	v_mov_b32_e32 v71, v80
	v_mov_b32_e32 v80, v73
	v_mov_b32_e32 v72, v6
	v_mov_b32_e32 v73, v14
	v_mov_b32_e32 v14, v7
	v_mov_b32_e32 v6, v8
	v_mov_b32_e32 v7, v16
	v_mov_b32_e32 v16, v9
	v_mov_b32_e32 v8, v58
	v_mov_b32_e32 v9, v18
	v_mov_b32_e32 v18, v59
	v_mov_b32_e32 v58, v60
	v_mov_b32_e32 v59, v20
	v_mov_b32_e32 v20, v61
	v_mov_b32_e32 v60, v66
	v_mov_b32_e32 v61, v26
	v_mov_b32_e32 v26, v67
	v_mov_b32_e32 v66, v68
	v_mov_b32_e32 v67, v28
	v_mov_b32_e32 v28, v69
	v_mov_b32_e32 v68, v74
	s_waitcnt lgkmcnt(0)
	v_mov_b32_e32 v69, v82
	v_mov_b32_e32 v82, v75
	v_mov_b32_e32 v74, v76
	v_mov_b32_e32 v75, v84
	v_mov_b32_e32 v84, v77
	s_waitcnt vmcnt(24)
	v_pk_fma_f32 v[40:41], v[116:117], v[86:87], v[40:41] op_sel_hi:[0,1,1]
	v_pk_fma_f32 v[12:13], v[116:117], v[12:13], v[42:43] op_sel_hi:[0,1,1]
	v_pk_fma_f32 v[42:43], v[116:117], v[56:57], v[44:45] op_sel_hi:[0,1,1]
	v_pk_fma_f32 v[38:39], v[116:117], v[64:65], v[38:39] op_sel_hi:[0,1,1]
	v_pk_fma_f32 v[2:3], v[118:119], v[2:3], v[40:41] op_sel_hi:[0,1,1]
	v_pk_fma_f32 v[12:13], v[118:119], v[22:23], v[12:13] op_sel_hi:[0,1,1]
	v_pk_fma_f32 v[22:23], v[118:119], v[30:31], v[42:43] op_sel_hi:[0,1,1]
	v_pk_fma_f32 v[30:31], v[118:119], v[78:79], v[38:39] op_sel_hi:[0,1,1]
	v_pk_fma_f32 v[2:3], v[120:121], v[10:11], v[2:3] op_sel_hi:[0,1,1]
	v_pk_fma_f32 v[10:11], v[120:121], v[54:55], v[12:13] op_sel_hi:[0,1,1]
	v_pk_fma_f32 v[12:13], v[120:121], v[62:63], v[22:23] op_sel_hi:[0,1,1]
	v_pk_fma_f32 v[22:23], v[120:121], v[70:71], v[30:31] op_sel_hi:[0,1,1]
	v_pk_fma_f32 v[2:3], v[122:123], v[4:5], v[2:3] op_sel_hi:[0,1,1]
	v_pk_fma_f32 v[4:5], v[122:123], v[24:25], v[10:11] op_sel_hi:[0,1,1]
	v_pk_fma_f32 v[10:11], v[122:123], v[32:33], v[12:13] op_sel_hi:[0,1,1]
	v_pk_fma_f32 v[12:13], v[122:123], v[80:81], v[22:23] op_sel_hi:[0,1,1]
	v_pk_fma_f32 v[2:3], v[124:125], v[72:73], v[2:3] op_sel_hi:[0,1,1]
	v_pk_fma_f32 v[4:5], v[124:125], v[8:9], v[4:5] op_sel_hi:[0,1,1]
	v_pk_fma_f32 v[8:9], v[124:125], v[60:61], v[10:11] op_sel_hi:[0,1,1]
	v_pk_fma_f32 v[10:11], v[124:125], v[68:69], v[12:13] op_sel_hi:[0,1,1]
	v_pk_fma_f32 v[2:3], v[126:127], v[14:15], v[2:3] op_sel_hi:[0,1,1]
	v_pk_fma_f32 v[4:5], v[126:127], v[18:19], v[4:5] op_sel_hi:[0,1,1]
	v_pk_fma_f32 v[8:9], v[126:127], v[26:27], v[8:9] op_sel_hi:[0,1,1]
	v_pk_fma_f32 v[10:11], v[126:127], v[82:83], v[10:11] op_sel_hi:[0,1,1]
	v_pk_fma_f32 v[2:3], v[128:129], v[6:7], v[2:3] op_sel_hi:[0,1,1]
	v_pk_fma_f32 v[4:5], v[128:129], v[58:59], v[4:5] op_sel_hi:[0,1,1]
	v_pk_fma_f32 v[6:7], v[128:129], v[66:67], v[8:9] op_sel_hi:[0,1,1]
	v_pk_fma_f32 v[8:9], v[128:129], v[74:75], v[10:11] op_sel_hi:[0,1,1]
	v_pk_fma_f32 v[40:41], v[130:131], v[16:17], v[2:3] op_sel_hi:[0,1,1]
	v_pk_fma_f32 v[42:43], v[130:131], v[20:21], v[4:5] op_sel_hi:[0,1,1]
	v_pk_fma_f32 v[44:45], v[130:131], v[28:29], v[6:7] op_sel_hi:[0,1,1]
	v_pk_fma_f32 v[38:39], v[130:131], v[84:85], v[8:9] op_sel_hi:[0,1,1]
	s_add_u32 s4, s4, 0x30000
	s_add_u32 s100, s4, 0x90000
	s_min_u32 s100, s100, 0x2d0000
	s_mov_b32 s101, 0
	v_lshl_add_u64 v[86:87], v[36:37], 0, s[100:101]
	v_add_co_u32_e32 v88, vcc, s11, v86
	s_nop 1
	v_addc_co_u32_e32 v89, vcc, 0, v87, vcc
	v_add_co_u32_e32 v90, vcc, s15, v86
	s_nop 1
	v_addc_co_u32_e32 v91, vcc, 0, v87, vcc
	v_add_co_u32_e32 v92, vcc, s16, v86
	s_nop 1
	v_addc_co_u32_e32 v93, vcc, 0, v87, vcc
	v_add_co_u32_e32 v94, vcc, s17, v86
	s_nop 1
	v_addc_co_u32_e32 v95, vcc, 0, v87, vcc
	v_add_co_u32_e32 v96, vcc, s18, v86
	s_nop 1
	v_addc_co_u32_e32 v97, vcc, 0, v87, vcc
	v_add_co_u32_e32 v98, vcc, s19, v86
	s_nop 1
	v_addc_co_u32_e32 v99, vcc, 0, v87, vcc
	global_load_dword v116, v[86:87], off
	global_load_dword v118, v[88:89], off
	global_load_dword v120, v[90:91], off
	global_load_dword v122, v[92:93], off
	global_load_dword v124, v[94:95], off
	global_load_dword v126, v[96:97], off
	global_load_dword v128, v[98:99], off
	v_add_co_u32_e32 v86, vcc, s20, v86
	s_nop 1
	v_addc_co_u32_e32 v87, vcc, 0, v87, vcc
	global_load_dword v130, v[86:87], off
	ds_read_b128 v[10:13], v52
	ds_read_b128 v[6:9], v52 offset:16
	ds_read_b128 v[2:5], v52 offset:4096
	ds_read_b128 v[14:17], v52 offset:4112
	ds_read_b128 v[54:57], v52 offset:8192
	ds_read_b128 v[58:61], v52 offset:8208
	ds_read_b128 v[22:25], v52 offset:12288
	ds_read_b128 v[18:21], v52 offset:12304
	ds_read_b128 v[62:65], v52 offset:16384
	ds_read_b128 v[66:69], v52 offset:16400
	ds_read_b128 v[30:33], v52 offset:20480
	ds_read_b128 v[26:29], v52 offset:20496
	ds_read_b128 v[70:73], v52 offset:24576
	ds_read_b128 v[74:77], v52 offset:24592
	ds_read_b128 v[78:81], v52 offset:28672
	ds_read_b128 v[82:85], v52 offset:28688
	v_add_u32_e32 v52, 32, v52
	s_waitcnt lgkmcnt(14)
	v_mov_b32_e32 v86, v10
	s_waitcnt lgkmcnt(13)
	v_mov_b32_e32 v87, v2
	v_mov_b32_e32 v2, v11
	v_mov_b32_e32 v10, v12
	v_mov_b32_e32 v11, v4
	v_mov_b32_e32 v4, v13
	s_waitcnt lgkmcnt(11)
	v_mov_b32_e32 v12, v54
	s_waitcnt lgkmcnt(9)
	v_mov_b32_e32 v13, v22
	v_mov_b32_e32 v22, v55
	v_mov_b32_e32 v54, v56
	v_mov_b32_e32 v55, v24
	v_mov_b32_e32 v24, v57
	s_waitcnt lgkmcnt(7)
	v_mov_b32_e32 v56, v62
	s_waitcnt lgkmcnt(5)
	v_mov_b32_e32 v57, v30
	v_mov_b32_e32 v30, v63
	v_mov_b32_e32 v62, v64
	v_mov_b32_e32 v63, v32
	v_mov_b32_e32 v32, v65
	s_waitcnt lgkmcnt(3)
	v_mov_b32_e32 v64, v70
	s_waitcnt lgkmcnt(1)
; DI void phase_mod(CP p, LAS unsigned char* lds) {
;     ...
;         for (int k = k0; k < k0 + 128; ++k) { const float w = W[(size_t)k * 6144];
; #pragma unroll
;             for (int b = 0; b < 8; ++b) acc[b] += ca[b * 1024 + k] * w; }
	v_mov_b32_e32 v65, v78
	v_mov_b32_e32 v78, v71
	v_mov_b32_e32 v70, v72
	v_mov_b32_e32 v71, v80
	v_mov_b32_e32 v80, v73
	v_mov_b32_e32 v72, v6
	v_mov_b32_e32 v73, v14
	v_mov_b32_e32 v14, v7
	v_mov_b32_e32 v6, v8
	v_mov_b32_e32 v7, v16
	v_mov_b32_e32 v16, v9
	v_mov_b32_e32 v8, v58
	v_mov_b32_e32 v9, v18
	v_mov_b32_e32 v18, v59
	v_mov_b32_e32 v58, v60
	v_mov_b32_e32 v59, v20
	v_mov_b32_e32 v20, v61
	v_mov_b32_e32 v60, v66
	v_mov_b32_e32 v61, v26
	v_mov_b32_e32 v26, v67
	v_mov_b32_e32 v66, v68
	v_mov_b32_e32 v67, v28
	v_mov_b32_e32 v28, v69
	v_mov_b32_e32 v68, v74
	s_waitcnt lgkmcnt(0)
	v_mov_b32_e32 v69, v82
	v_mov_b32_e32 v82, v75
	v_mov_b32_e32 v74, v76
	v_mov_b32_e32 v75, v84
	v_mov_b32_e32 v84, v77
	s_waitcnt vmcnt(24)
	v_pk_fma_f32 v[40:41], v[132:133], v[86:87], v[40:41] op_sel_hi:[0,1,1]
	v_pk_fma_f32 v[12:13], v[132:133], v[12:13], v[42:43] op_sel_hi:[0,1,1]
	v_pk_fma_f32 v[42:43], v[132:133], v[56:57], v[44:45] op_sel_hi:[0,1,1]
	v_pk_fma_f32 v[38:39], v[132:133], v[64:65], v[38:39] op_sel_hi:[0,1,1]
	v_pk_fma_f32 v[2:3], v[134:135], v[2:3], v[40:41] op_sel_hi:[0,1,1]
	v_pk_fma_f32 v[12:13], v[134:135], v[22:23], v[12:13] op_sel_hi:[0,1,1]
	v_pk_fma_f32 v[22:23], v[134:135], v[30:31], v[42:43] op_sel_hi:[0,1,1]
	v_pk_fma_f32 v[30:31], v[134:135], v[78:79], v[38:39] op_sel_hi:[0,1,1]
	v_pk_fma_f32 v[2:3], v[136:137], v[10:11], v[2:3] op_sel_hi:[0,1,1]
	v_pk_fma_f32 v[10:11], v[136:137], v[54:55], v[12:13] op_sel_hi:[0,1,1]
	v_pk_fma_f32 v[12:13], v[136:137], v[62:63], v[22:23] op_sel_hi:[0,1,1]
	v_pk_fma_f32 v[22:23], v[136:137], v[70:71], v[30:31] op_sel_hi:[0,1,1]
	v_pk_fma_f32 v[2:3], v[138:139], v[4:5], v[2:3] op_sel_hi:[0,1,1]
	v_pk_fma_f32 v[4:5], v[138:139], v[24:25], v[10:11] op_sel_hi:[0,1,1]
	v_pk_fma_f32 v[10:11], v[138:139], v[32:33], v[12:13] op_sel_hi:[0,1,1]
	v_pk_fma_f32 v[12:13], v[138:139], v[80:81], v[22:23] op_sel_hi:[0,1,1]
	v_pk_fma_f32 v[2:3], v[140:141], v[72:73], v[2:3] op_sel_hi:[0,1,1]
	v_pk_fma_f32 v[4:5], v[140:141], v[8:9], v[4:5] op_sel_hi:[0,1,1]
	v_pk_fma_f32 v[8:9], v[140:141], v[60:61], v[10:11] op_sel_hi:[0,1,1]
	v_pk_fma_f32 v[10:11], v[140:141], v[68:69], v[12:13] op_sel_hi:[0,1,1]
	v_pk_fma_f32 v[2:3], v[142:143], v[14:15], v[2:3] op_sel_hi:[0,1,1]
	v_pk_fma_f32 v[4:5], v[142:143], v[18:19], v[4:5] op_sel_hi:[0,1,1]
	v_pk_fma_f32 v[8:9], v[142:143], v[26:27], v[8:9] op_sel_hi:[0,1,1]
	v_pk_fma_f32 v[10:11], v[142:143], v[82:83], v[10:11] op_sel_hi:[0,1,1]
	v_pk_fma_f32 v[2:3], v[144:145], v[6:7], v[2:3] op_sel_hi:[0,1,1]
	v_pk_fma_f32 v[4:5], v[144:145], v[58:59], v[4:5] op_sel_hi:[0,1,1]
	v_pk_fma_f32 v[6:7], v[144:145], v[66:67], v[8:9] op_sel_hi:[0,1,1]
	v_pk_fma_f32 v[8:9], v[144:145], v[74:75], v[10:11] op_sel_hi:[0,1,1]
	v_pk_fma_f32 v[40:41], v[146:147], v[16:17], v[2:3] op_sel_hi:[0,1,1]
	v_pk_fma_f32 v[42:43], v[146:147], v[20:21], v[4:5] op_sel_hi:[0,1,1]
	v_pk_fma_f32 v[44:45], v[146:147], v[28:29], v[6:7] op_sel_hi:[0,1,1]
	v_pk_fma_f32 v[38:39], v[146:147], v[84:85], v[8:9] op_sel_hi:[0,1,1]
	s_add_u32 s4, s4, 0x30000
	s_add_u32 s100, s4, 0x90000
	s_min_u32 s100, s100, 0x2d0000
	s_mov_b32 s101, 0
	v_lshl_add_u64 v[86:87], v[36:37], 0, s[100:101]
	v_add_co_u32_e32 v88, vcc, s11, v86
	s_nop 1
	v_addc_co_u32_e32 v89, vcc, 0, v87, vcc
	v_add_co_u32_e32 v90, vcc, s15, v86
	s_nop 1
	v_addc_co_u32_e32 v91, vcc, 0, v87, vcc
	v_add_co_u32_e32 v92, vcc, s16, v86
	s_nop 1
	v_addc_co_u32_e32 v93, vcc, 0, v87, vcc
	v_add_co_u32_e32 v94, vcc, s17, v86
	s_nop 1
	v_addc_co_u32_e32 v95, vcc, 0, v87, vcc
	v_add_co_u32_e32 v96, vcc, s18, v86
	s_nop 1
	v_addc_co_u32_e32 v97, vcc, 0, v87, vcc
	v_add_co_u32_e32 v98, vcc, s19, v86
	s_nop 1
	v_addc_co_u32_e32 v99, vcc, 0, v87, vcc
	global_load_dword v132, v[86:87], off
	global_load_dword v134, v[88:89], off
	global_load_dword v136, v[90:91], off
	global_load_dword v138, v[92:93], off
	global_load_dword v140, v[94:95], off
	global_load_dword v142, v[96:97], off
	global_load_dword v144, v[98:99], off
	v_add_co_u32_e32 v86, vcc, s20, v86
	s_nop 1
	v_addc_co_u32_e32 v87, vcc, 0, v87, vcc
	global_load_dword v146, v[86:87], off
	ds_read_b128 v[10:13], v52
	ds_read_b128 v[6:9], v52 offset:16
	ds_read_b128 v[2:5], v52 offset:4096
	ds_read_b128 v[14:17], v52 offset:4112
	ds_read_b128 v[54:57], v52 offset:8192
	ds_read_b128 v[58:61], v52 offset:8208
	ds_read_b128 v[22:25], v52 offset:12288
	ds_read_b128 v[18:21], v52 offset:12304
	ds_read_b128 v[62:65], v52 offset:16384
	ds_read_b128 v[66:69], v52 offset:16400
	ds_read_b128 v[30:33], v52 offset:20480
	ds_read_b128 v[26:29], v52 offset:20496
	ds_read_b128 v[70:73], v52 offset:24576
	ds_read_b128 v[74:77], v52 offset:24592
	ds_read_b128 v[78:81], v52 offset:28672
	ds_read_b128 v[82:85], v52 offset:28688
	v_add_u32_e32 v52, 32, v52
	s_waitcnt lgkmcnt(14)
	v_mov_b32_e32 v86, v10
	s_waitcnt lgkmcnt(13)
	v_mov_b32_e32 v87, v2
	v_mov_b32_e32 v2, v11
	v_mov_b32_e32 v10, v12
	v_mov_b32_e32 v11, v4
	v_mov_b32_e32 v4, v13
	s_waitcnt lgkmcnt(11)
; DI void phase_mod(CP p, LAS unsigned char* lds) {
;     ...
;         for (int k = k0; k < k0 + 128; ++k) { const float w = W[(size_t)k * 6144];
; #pragma unroll
;             for (int b = 0; b < 8; ++b) acc[b] += ca[b * 1024 + k] * w; }
; #pragma unroll
;         for (int b = 0; b < 8; ++b) red[(wave * 8 + b) * 64 + lane] = acc[b];
;         __syncthreads();
;         { const int b = tid >> 6; float s = 0.f;
; #pragma unroll
;           for (int w = 0; w < 8; ++w) s += red[(w * 8 + b) * 64 + lane];
;           mod[(size_t)(l * 8 + b) * 6144 + n] = s + p->b_ada[l * 6144 + n]; }
;         __syncthreads();
	v_mov_b32_e32 v12, v54
	s_waitcnt lgkmcnt(9)
	v_mov_b32_e32 v13, v22
	v_mov_b32_e32 v22, v55
	v_mov_b32_e32 v54, v56
	v_mov_b32_e32 v55, v24
	v_mov_b32_e32 v24, v57
	s_waitcnt lgkmcnt(7)
	v_mov_b32_e32 v56, v62
	s_waitcnt lgkmcnt(5)
	v_mov_b32_e32 v57, v30
	v_mov_b32_e32 v30, v63
	v_mov_b32_e32 v62, v64
	v_mov_b32_e32 v63, v32
	v_mov_b32_e32 v32, v65
	s_waitcnt lgkmcnt(3)
	v_mov_b32_e32 v64, v70
	s_waitcnt lgkmcnt(1)
	v_mov_b32_e32 v65, v78
	v_mov_b32_e32 v78, v71
	v_mov_b32_e32 v70, v72
	v_mov_b32_e32 v71, v80
	v_mov_b32_e32 v80, v73
	v_mov_b32_e32 v72, v6
	v_mov_b32_e32 v73, v14
	v_mov_b32_e32 v14, v7
	v_mov_b32_e32 v6, v8
	v_mov_b32_e32 v7, v16
	v_mov_b32_e32 v16, v9
	v_mov_b32_e32 v8, v58
	v_mov_b32_e32 v9, v18
	v_mov_b32_e32 v18, v59
	v_mov_b32_e32 v58, v60
	v_mov_b32_e32 v59, v20
	v_mov_b32_e32 v20, v61
	v_mov_b32_e32 v60, v66
	v_mov_b32_e32 v61, v26
	v_mov_b32_e32 v26, v67
	v_mov_b32_e32 v66, v68
	v_mov_b32_e32 v67, v28
	v_mov_b32_e32 v28, v69
	v_mov_b32_e32 v68, v74
	s_waitcnt lgkmcnt(0)
	v_mov_b32_e32 v69, v82
	v_mov_b32_e32 v82, v75
	v_mov_b32_e32 v74, v76
	v_mov_b32_e32 v75, v84
	v_mov_b32_e32 v84, v77
	s_waitcnt vmcnt(24)
	v_pk_fma_f32 v[40:41], v[148:149], v[86:87], v[40:41] op_sel_hi:[0,1,1]
	v_pk_fma_f32 v[12:13], v[148:149], v[12:13], v[42:43] op_sel_hi:[0,1,1]
	v_pk_fma_f32 v[42:43], v[148:149], v[56:57], v[44:45] op_sel_hi:[0,1,1]
	v_pk_fma_f32 v[38:39], v[148:149], v[64:65], v[38:39] op_sel_hi:[0,1,1]
	v_pk_fma_f32 v[2:3], v[150:151], v[2:3], v[40:41] op_sel_hi:[0,1,1]
	v_pk_fma_f32 v[12:13], v[150:151], v[22:23], v[12:13] op_sel_hi:[0,1,1]
	v_pk_fma_f32 v[22:23], v[150:151], v[30:31], v[42:43] op_sel_hi:[0,1,1]
	v_pk_fma_f32 v[30:31], v[150:151], v[78:79], v[38:39] op_sel_hi:[0,1,1]
	v_pk_fma_f32 v[2:3], v[152:153], v[10:11], v[2:3] op_sel_hi:[0,1,1]
	v_pk_fma_f32 v[10:11], v[152:153], v[54:55], v[12:13] op_sel_hi:[0,1,1]
	v_pk_fma_f32 v[12:13], v[152:153], v[62:63], v[22:23] op_sel_hi:[0,1,1]
	v_pk_fma_f32 v[22:23], v[152:153], v[70:71], v[30:31] op_sel_hi:[0,1,1]
	v_pk_fma_f32 v[2:3], v[154:155], v[4:5], v[2:3] op_sel_hi:[0,1,1]
	v_pk_fma_f32 v[4:5], v[154:155], v[24:25], v[10:11] op_sel_hi:[0,1,1]
	v_pk_fma_f32 v[10:11], v[154:155], v[32:33], v[12:13] op_sel_hi:[0,1,1]
	v_pk_fma_f32 v[12:13], v[154:155], v[80:81], v[22:23] op_sel_hi:[0,1,1]
	v_pk_fma_f32 v[2:3], v[156:157], v[72:73], v[2:3] op_sel_hi:[0,1,1]
	v_pk_fma_f32 v[4:5], v[156:157], v[8:9], v[4:5] op_sel_hi:[0,1,1]
	v_pk_fma_f32 v[8:9], v[156:157], v[60:61], v[10:11] op_sel_hi:[0,1,1]
	v_pk_fma_f32 v[10:11], v[156:157], v[68:69], v[12:13] op_sel_hi:[0,1,1]
	v_pk_fma_f32 v[2:3], v[158:159], v[14:15], v[2:3] op_sel_hi:[0,1,1]
	v_pk_fma_f32 v[4:5], v[158:159], v[18:19], v[4:5] op_sel_hi:[0,1,1]
	v_pk_fma_f32 v[8:9], v[158:159], v[26:27], v[8:9] op_sel_hi:[0,1,1]
	v_pk_fma_f32 v[10:11], v[158:159], v[82:83], v[10:11] op_sel_hi:[0,1,1]
	v_pk_fma_f32 v[2:3], v[160:161], v[6:7], v[2:3] op_sel_hi:[0,1,1]
	v_pk_fma_f32 v[4:5], v[160:161], v[58:59], v[4:5] op_sel_hi:[0,1,1]
	v_pk_fma_f32 v[6:7], v[160:161], v[66:67], v[8:9] op_sel_hi:[0,1,1]
	v_pk_fma_f32 v[8:9], v[160:161], v[74:75], v[10:11] op_sel_hi:[0,1,1]
	v_pk_fma_f32 v[40:41], v[162:163], v[16:17], v[2:3] op_sel_hi:[0,1,1]
	v_pk_fma_f32 v[42:43], v[162:163], v[20:21], v[4:5] op_sel_hi:[0,1,1]
	v_pk_fma_f32 v[44:45], v[162:163], v[28:29], v[6:7] op_sel_hi:[0,1,1]
	v_pk_fma_f32 v[38:39], v[162:163], v[84:85], v[8:9] op_sel_hi:[0,1,1]
	s_add_u32 s4, s4, 0x30000
	s_cmp_eq_u32 s4, 0x300000
	s_cbranch_scc0 .Lmod_loop
	s_mul_i32 s4, s22, 0xffffffa0
	s_add_i32 s4, s4, s21
	v_lshl_or_b32 v2, s4, 6, v1
	v_add_u32_e32 v4, s23, v2
	v_ashrrev_i32_e32 v5, 31, v4
	v_lshl_add_u64 v[4:5], v[4:5], 2, s[6:7]
	ds_write2st64_b32 v51, v40, v41 offset0:128 offset1:129
	ds_write2st64_b32 v51, v42, v43 offset0:130 offset1:131
	ds_write2st64_b32 v51, v44, v45 offset0:132 offset1:133
	ds_write2st64_b32 v51, v38, v39 offset0:134 offset1:135
	s_waitcnt lgkmcnt(0)
	s_barrier
	global_load_dword v14, v[4:5], off
	ds_read2st64_b32 v[4:5], v47 offset0:128 offset1:136
	ds_read2st64_b32 v[6:7], v47 offset0:144 offset1:152
	ds_read2st64_b32 v[8:9], v47 offset0:160 offset1:168
	ds_read2st64_b32 v[10:11], v47 offset0:176 offset1:184
	v_lshl_add_u32 v3, s22, 3, v46
	s_waitcnt lgkmcnt(3)
	v_add_f32_e32 v4, 0, v4
	v_add_f32_e32 v4, v4, v5
	s_waitcnt lgkmcnt(2)
	v_add_f32_e32 v4, v4, v6
	v_add_f32_e32 v4, v4, v7
	s_waitcnt lgkmcnt(1)
	v_add_f32_e32 v4, v4, v8
	v_add_f32_e32 v4, v4, v9
	v_mov_b64_e32 v[12:13], s[12:13]
	s_waitcnt lgkmcnt(0)
	v_add_f32_e32 v4, v4, v10
	v_mad_i64_i32 v[12:13], s[4:5], v3, s11, v[12:13]
	s_add_i32 s21, s21, s66
	v_ashrrev_i32_e32 v3, 31, v2
	v_add_f32_e32 v4, v4, v11
	s_cmpk_gt_i32 s21, 0x17f
	v_lshl_add_u64 v[2:3], v[2:3], 2, v[12:13]
	v_add_u32_e32 v48, s14, v48
	s_waitcnt vmcnt(0)
	v_add_f32_e32 v4, v4, v14
	global_store_dword v[2:3], v4, off
	s_barrier
	s_cbranch_scc0 .LBB0_10

; DI unsigned pk2(float lo, float hi) { f32x2_t v = {lo, hi}; bf16x2_t b = __builtin_convertvector(v, bf16x2_t); return __builtin_bit_cast(unsigned, b); }
; #define MFMA16(a, b, c) __builtin_amdgcn_mfma_f32_16x16x32_bf16((a), (b), (c), 0, 0, 0)
; DI void kv_chunk(CP p, int b, int n, LAS unsigned char* lds) {
;     ...
;         u32x4 gv0, gv1, gk; f32x4 c0, c1, e0, e1;
;         const float* bcb = (const float*)(p->ws + WS_BCUM) + (size_t)tok0 * 256;
;     ...
;         KVG_LOAD(0);
;     ...
;             for (int x = 0; x < 4; ++x) { f32x4 acc = {0.f, 0.f, 0.f, 0.f};
; #pragma unroll
;                 for (int ks = 0; ks < 2; ++ks) acc = MFMA16(a[ks], bb[x][ks], acc);
;                 u32x2 wv; wv.x = pk2(acc[0], acc[1]); wv.y = pk2(acc[2], acc[3]);
;                 *(u32x2*)(st + (size_t)(16 * (et0 + x) + lr) * 64 + 16 * dt + 4 * g) = wv; }
.LBB0_305:
	s_add_i32 s100, s64, -32
	s_mov_b32 s101, 0
	s_lshl_b64 s[100:101], s[100:101], 15
	v_lshl_add_u64 v[70:71], v[68:69], 0, s[100:101]
	s_mov_b64 s[100:101], 0x2000
	v_lshl_add_u64 v[88:89], v[70:71], 0, s[100:101]
	v_lshl_add_u64 v[90:91], v[88:89], 0, s[100:101]
	v_lshl_add_u64 v[92:93], v[90:91], 0, s[100:101]
	ds_read_b128 v[72:75], v65
	ds_read_b128 v[76:79], v65 offset:8704
	ds_read_b128 v[80:83], v65 offset:17408
	ds_read_b128 v[84:87], v65 offset:26112
	s_waitcnt lgkmcnt(3)
	global_store_dwordx4 v[70:71], v[72:75], off
	s_waitcnt lgkmcnt(2)
	global_store_dwordx4 v[88:89], v[76:79], off
	s_waitcnt lgkmcnt(1)
	global_store_dwordx4 v[90:91], v[80:83], off
	s_waitcnt lgkmcnt(0)
	global_store_dwordx4 v[92:93], v[84:87], off
	s_or_b32 s52, s56, s55
	s_lshl_b64 s[48:49], s[48:49], 10
	v_readlane_b32 s53, v254, 40
	s_add_u32 s56, s53, s48
	v_readlane_b32 s48, v254, 41
	s_waitcnt vmcnt(9)
	v_lshlrev_b32_e32 v8, 1, v18
	v_mov_b32_e32 v9, v197
	s_addc_u32 s57, s48, s49
	v_lshl_add_u64 v[8:9], s[50:51], 0, v[8:9]
	s_add_u32 s48, s50, 0x2c00
	v_lshl_add_u64 v[38:39], v[16:17], 1, v[8:9]
	s_addc_u32 s49, s51, 0
	v_lshl_add_u64 v[36:37], v[16:17], 2, s[56:57]
	v_add_co_u32_e32 v8, vcc, s33, v38
	s_mov_b64 s[50:51], 0xfc00
	s_nop 0
	v_addc_co_u32_e32 v9, vcc, 0, v39, vcc
	v_lshl_add_u64 v[24:25], v[36:37], 0, s[50:51]
	s_mov_b32 s50, 0xf000
	v_lshl_add_u64 v[0:1], v[28:29], 1, s[48:49]
	v_lshlrev_b32_e32 v196, 1, v20
	v_lshl_add_u64 v[2:3], v[30:31], 1, s[48:49]
	v_lshlrev_b32_e32 v10, 10, v32
	v_mov_b32_e32 v11, v197
	v_add_co_u32_e32 v16, vcc, s50, v36
	v_lshl_add_u64 v[0:1], v[0:1], 0, v[196:197]
	v_lshl_add_u64 v[4:5], v[2:3], 0, v[196:197]
	v_lshl_add_u64 v[20:21], v[36:37], 0, v[10:11]
	v_addc_co_u32_e32 v17, vcc, 0, v37, vcc
	global_load_dwordx4 v[0:3], v[0:1], off
	s_nop 0
	global_load_dwordx4 v[4:7], v[4:5], off
	s_nop 0
	global_load_dwordx4 v[8:11], v[8:9], off offset:2560
	s_nop 0
	global_load_dwordx4 v[12:15], v[20:21], off
	s_nop 0
	global_load_dwordx4 v[16:19], v[16:17], off offset:3072
	s_nop 0
	global_load_dwordx4 v[20:23], v[20:21], off offset:16
	s_nop 0
	global_load_dwordx4 v[24:27], v[24:25], off offset:16
	s_and_b32 s53, s60, 48
	s_mov_b64 s[50:51], 0x2a00
	v_lshlrev_b32_e32 v46, 8, v32
	v_or_b32_e32 v32, s53, v44
	s_movk_i32 s55, 0x90
	v_lshl_add_u64 v[38:39], v[38:39], 0, s[50:51]
	s_and_b32 s51, s22, -4
	v_mad_u32_u24 v51, v32, s55, 0
	s_lshl_b32 s53, s53, 1
	v_readlane_b32 s55, v254, 63
	s_add_u32 s56, s55, s53
	v_readlane_b32 s53, v255, 0
	s_addc_u32 s57, s53, 0
	s_or_b32 s53, s51, 1
	s_or_b32 s55, s51, 2
	s_or_b32 s22, s22, 3
	v_lshlrev_b32_e32 v32, 1, v34
	v_lshl_or_b32 v34, s51, 4, v44
	v_lshl_or_b32 v40, s53, 4, v44
	v_lshl_or_b32 v42, s55, 4, v44
	v_lshl_or_b32 v44, s22, 4, v44
	v_mov_b32_e32 v33, v197
	v_lshl_add_u32 v52, s51, 5, v35
	v_lshl_add_u32 v53, s53, 5, v35
	v_lshl_add_u32 v54, s55, 5, v35
	v_lshl_add_u32 v55, s22, 5, v35
	v_ashrrev_i32_e32 v35, 31, v34
	v_ashrrev_i32_e32 v41, 31, v40
	v_ashrrev_i32_e32 v43, 31, v42
	v_ashrrev_i32_e32 v45, 31, v44
	s_mov_b32 s50, 0
	v_lshl_add_u64 v[32:33], s[56:57], 0, v[32:33]
	v_lshlrev_b64 v[34:35], 7, v[34:35]
	v_lshlrev_b64 v[40:41], 7, v[40:41]
	v_lshlrev_b64 v[42:43], 7, v[42:43]
	v_lshlrev_b64 v[44:45], 7, v[44:45]
	v_lshlrev_b32_e32 v46, 2, v46
	v_add_u32_e32 v51, v51, v47
	v_add_u32_e32 v52, v52, v50
	v_add_u32_e32 v53, v53, v50
	v_add_u32_e32 v54, v54, v50
	v_add_u32_e32 v50, v55, v50
	v_readlane_b32 s65, v253, 53
	v_bfe_u32 v101, v199, 6, 2
	v_lshlrev_b32_e32 v101, 5, v101
	v_bfe_u32 v114, v199, 4, 2
	v_lshl_add_u32 v101, v114, 3, v101
	v_add_u32_e32 v114, 0x12800, v101
	v_lshrrev_b32_e32 v115, 7, v34
	v_mul_u32_u24_e32 v115, 0x90, v115
	v_add_u32_e32 v94, v115, v114
	v_lshrrev_b32_e32 v115, 7, v40
	v_mul_u32_u24_e32 v115, 0x90, v115
	v_add_u32_e32 v95, v115, v114
	v_lshrrev_b32_e32 v115, 7, v42
	v_mul_u32_u24_e32 v115, 0x90, v115
	v_add_u32_e32 v96, v115, v114
	v_lshrrev_b32_e32 v115, 7, v44
	v_mul_u32_u24_e32 v115, 0x90, v115
	v_add_u32_e32 v97, v115, v114
	v_lshrrev_b32_e32 v115, 3, v199
	v_mul_u32_u24_e32 v100, 0x90, v115
	v_and_b32_e32 v115, 7, v199
	v_lshl_add_u32 v100, v115, 4, v100
	v_add_u32_e32 v100, 0x12800, v100
	v_lshlrev_b32_e32 v114, 4, v199
	v_sub_u32_e32 v114, v114, v101
	v_ashrrev_i32_e32 v115, 31, v114
	v_lshl_add_u64 v[98:99], v[32:33], 0, v[114:115]
	s_branch .LBB0_307
; #define LAS __attribute__((address_space(3)))
; DI unsigned pk2(float lo, float hi) { f32x2_t v = {lo, hi}; bf16x2_t b = __builtin_convertvector(v, bf16x2_t); return __builtin_bit_cast(unsigned, b); }
; #define MFMA16(a, b, c) __builtin_amdgcn_mfma_f32_16x16x32_bf16((a), (b), (c), 0, 0, 0)
; DI void kv_chunk(CP p, int b, int n, LAS unsigned char* lds) {
;     ...
;         for (int h = 0; h < 4; ++h) {
;             *(LAS u32x4*)(lds + VT + (tid >> 4) * 272 + (tid & 15) * 16) = gv0; *(LAS u32x4*)(lds + VT + (32 + (tid >> 4)) * 272 + (tid & 15) * 16) = gv1;
;             { float x[8]; unpack8(gk, x);
;               const float wd[8] = {e0.x - c0.x, e0.y - c0.y, e0.z - c0.z, e0.w - c0.w, e1.x - c1.x, e1.y - c1.y, e1.z - c1.z, e1.w - c1.w};
; #pragma unroll
;               for (int e = 0; e < 8; ++e) *(LAS bf16*)(lds + KT + (kpt * 8 + e) * 144 + kj * 2) = (bf16)(pk2(x[e] * __expf(wd[e]), 0.f) & 0xffffu); }
;             if (h < 3) KVG_LOAD(h + 1);
;             __syncthreads();
;             const int dt = wave & 3, et0 = (wave >> 2) * 4;
;             bf16x8 a[2];
; #pragma unroll
;             for (int ks = 0; ks < 2; ++ks) a[ks] = *(const LAS bf16x8*)(lds + KT + (16 * dt + lr) * 144 + ks * 64 + g * 16);
;             bf16* st = (bf16*)(p->ws + WS_GST) + (size_t)((((b * 4 + h) << 5) + n)) * 128 * 64;
;             bf16x8 bb[4][2];
; #pragma unroll
;             for (int x = 0; x < 4; ++x)
; #pragma unroll
;                 for (int ks = 0; ks < 2; ++ks) {
;                     const LAS unsigned char* vp_ = lds + VT + (32 * ks + 8 * g + (lr >> 2)) * 272 + (et0 + x) * 32 + 8 * (lr & 3);
;                     const v4i16_t lo = __builtin_amdgcn_ds_read_tr16_b64_v4i16((LAS v4i16_t*)vp_), hi = __builtin_amdgcn_ds_read_tr16_b64_v4i16((LAS v4i16_t*)(vp_ + 4 * 272));
;                     bb[x][ks] = (bf16x8){lo[0], lo[1], lo[2], lo[3], hi[0], hi[1], hi[2], hi[3]}; }
; #pragma unroll
;             for (int x = 0; x < 4; ++x) { f32x4 acc = {0.f, 0.f, 0.f, 0.f};
; #pragma unroll
;                 for (int ks = 0; ks < 2; ++ks) acc = MFMA16(a[ks], bb[x][ks], acc);
;                 u32x2 wv; wv.x = pk2(acc[0], acc[1]); wv.y = pk2(acc[2], acc[3]);
;                 *(u32x2*)(st + (size_t)(16 * (et0 + x) + lr) * 64 + 16 * dt + 4 * g) = wv; }
;             __syncthreads();
;         }
.LBB0_306:
	s_waitcnt lgkmcnt(0)
	s_barrier
	ds_read_b128 v[56:59], v51 offset:18432
	ds_read_b128 v[60:63], v51 offset:18496
	ds_read_b64_tr_b16 v[162:163], v52
	ds_read_b64_tr_b16 v[164:165], v52 offset:1088
	ds_read_b64_tr_b16 v[166:167], v52 offset:8704
	ds_read_b64_tr_b16 v[168:169], v52 offset:9792
	s_waitcnt lgkmcnt(2)
	v_mfma_f32_16x16x32_bf16 v[162:165], v[56:59], v[162:165], 0
	ds_read_b64_tr_b16 v[180:181], v53
	ds_read_b64_tr_b16 v[182:183], v53 offset:1088
	ds_read_b64_tr_b16 v[200:201], v53 offset:8704
	ds_read_b64_tr_b16 v[202:203], v53 offset:9792
	s_lshl_b32 s22, s50, 5
	s_add_i32 s56, s22, s52
	s_waitcnt lgkmcnt(4)
	v_mfma_f32_16x16x32_bf16 v[162:165], v[60:63], v[166:169], v[162:165]
	ds_read_b64_tr_b16 v[166:167], v54
	ds_read_b64_tr_b16 v[168:169], v54 offset:1088
	ds_read_b64_tr_b16 v[204:205], v54 offset:8704
	ds_read_b64_tr_b16 v[206:207], v54 offset:9792
	ds_read_b64_tr_b16 v[208:209], v50
	ds_read_b64_tr_b16 v[210:211], v50 offset:1088
	ds_read_b64_tr_b16 v[216:217], v50 offset:8704
	ds_read_b64_tr_b16 v[218:219], v50 offset:9792
	s_ashr_i32 s57, s56, 31
	s_waitcnt lgkmcnt(10)
	v_mfma_f32_16x16x32_bf16 v[180:183], v[56:59], v[180:183], 0
	s_lshl_b64 s[56:57], s[56:57], 14
	v_lshl_add_u64 v[220:221], v[32:33], 0, s[56:57]
	s_cmp_lg_u32 s51, 4
	s_waitcnt lgkmcnt(8)
	v_mfma_f32_16x16x32_bf16 v[180:183], v[60:63], v[200:203], v[180:183]
	v_cvt_pk_bf16_f32 v200, v162, v163
	v_cvt_pk_bf16_f32 v201, v164, v165
	v_lshl_add_u64 v[202:203], v[220:221], 0, v[34:35]
	s_waitcnt lgkmcnt(6)
	v_mfma_f32_16x16x32_bf16 v[162:165], v[56:59], v[166:169], 0
	v_lshl_add_u64 v[168:169], v[220:221], 0, v[40:41]
	s_nop 1
	v_cvt_pk_bf16_f32 v166, v180, v181
	v_cvt_pk_bf16_f32 v167, v182, v183
	s_waitcnt lgkmcnt(2)
	v_mfma_f32_16x16x32_bf16 v[56:59], v[56:59], v[208:211], 0
	s_mov_b32 s50, s51
	ds_write_b64 v94, v[200:201]
	ds_write_b64 v95, v[166:167]
	v_mfma_f32_16x16x32_bf16 v[162:165], v[60:63], v[204:207], v[162:165]
	s_waitcnt lgkmcnt(0)
	v_mfma_f32_16x16x32_bf16 v[56:59], v[60:63], v[216:219], v[56:59]
	s_nop 5
	v_cvt_pk_bf16_f32 v162, v162, v163
	v_cvt_pk_bf16_f32 v163, v164, v165
	v_lshl_add_u64 v[164:165], v[220:221], 0, v[42:43]
	v_cvt_pk_bf16_f32 v56, v56, v57
	v_cvt_pk_bf16_f32 v57, v58, v59
	v_lshl_add_u64 v[58:59], v[220:221], 0, v[44:45]
	ds_write_b64 v96, v[162:163]
	ds_write_b64 v97, v[56:57]
	s_waitcnt lgkmcnt(0)
	s_barrier
	s_cbranch_scc1 .Lgla_cont
	s_add_i32 s100, s50, -1
	s_lshl_b32 s100, s100, 5
	s_add_i32 s100, s100, s52
	s_mov_b32 s101, 0
	s_lshl_b64 s[100:101], s[100:101], 14
	v_lshl_add_u64 v[102:103], v[98:99], 0, s[100:101]
	s_mov_b64 s[100:101], 0x2000
	v_lshl_add_u64 v[104:105], v[102:103], 0, s[100:101]
	ds_read_b128 v[106:109], v100
	ds_read_b128 v[110:113], v100 offset:9216
	s_waitcnt lgkmcnt(1)
	global_store_dwordx4 v[102:103], v[106:109], off
	s_waitcnt lgkmcnt(0)
	global_store_dwordx4 v[104:105], v[110:113], off
	s_branch .LBB0_266
.Lgla_cont:
.LBB0_307:
	s_waitcnt vmcnt(2)
	v_sub_f32_e32 v62, v16, v12
	v_mul_f32_e32 v62, 0x3fb8aa3b, v62
	v_sub_f32_e32 v63, v17, v13
	v_exp_f32_e32 v62, v62
	v_mul_f32_e32 v63, 0x3fb8aa3b, v63
	v_exp_f32_e32 v63, v63
	v_lshlrev_b32_e32 v47, 16, v8
	v_mul_f32_e32 v47, v62, v47
	v_and_b32_e32 v55, 0xffff0000, v8
	v_cvt_pk_bf16_f32 v47, v47, s0
	ds_write_b128 v48, v[0:3]
	ds_write_b128 v48, v[4:7] offset:8704
	ds_write_b16 v49, v47 offset:18432
	v_mul_f32_e32 v47, v63, v55
	v_sub_f32_e32 v143, v18, v14
	v_sub_f32_e32 v145, v19, v15
	v_cvt_pk_bf16_f32 v47, v47, s0
	v_mul_f32_e32 v55, 0x3fb8aa3b, v143
	ds_write_b16 v49, v47 offset:18576
	v_mul_f32_e32 v47, 0x3fb8aa3b, v145
	v_exp_f32_e32 v55, v55
	v_exp_f32_e32 v47, v47
	v_lshlrev_b32_e32 v56, 16, v9
	v_and_b32_e32 v57, 0xffff0000, v9
	v_mul_f32_e32 v55, v55, v56
	v_mul_f32_e32 v47, v47, v57
	s_waitcnt vmcnt(0)
	s_cmp_eq_u32 s50, 0
	s_cbranch_scc1 .Lkvl2_skip
	s_add_i32 s100, s50, -1
	s_lshl_b32 s100, s100, 5
	s_add_i32 s100, s100, s52
	s_mov_b32 s101, 0
	s_lshl_b64 s[100:101], s[100:101], 14
	v_lshl_add_u64 v[102:103], v[98:99], 0, s[100:101]
	s_mov_b64 s[100:101], 0x2000
	v_lshl_add_u64 v[104:105], v[102:103], 0, s[100:101]
	ds_read_b128 v[106:109], v100
	ds_read_b128 v[110:113], v100 offset:9216
	s_waitcnt lgkmcnt(1)
	global_store_dwordx4 v[102:103], v[106:109], off
	s_waitcnt lgkmcnt(0)
	global_store_dwordx4 v[104:105], v[110:113], off
